# speedup vs baseline: 1.0047x; 1.0047x over previous
.LBB0_254:
	v_add_u32_e32 v188, v239, v238
	ds_read_b128 v[132:135], v188
	ds_read_b128 v[136:139], v188 offset:1024
	ds_read_b128 v[140:143], v188 offset:2048
	ds_read_b128 v[144:147], v188 offset:3072
	s_add_i32 s71, s58, s70
	v_readfirstlane_b32 s47, v241
	s_add_i32 s46, s71, 0xffffff80
	s_mov_b32 m0, s47
	s_add_i32 vcc_lo, s85, s70
	v_readfirstlane_b32 s47, v240
	ds_read_b128 v[148:151], v237
	ds_read_b128 v[152:155], v237 offset:1024
	ds_read_b128 v[156:159], v237 offset:2048
	ds_read_b128 v[160:163], v237 offset:3072
	ds_read_b128 v[164:167], v237 offset:4096
	ds_read_b128 v[168:171], v237 offset:5120
	ds_read_b128 v[172:175], v237 offset:6144
	ds_read_b128 v[176:179], v237 offset:7168
	buffer_load_dwordx4 v0, s[24:27], s46 offen lds
	s_add_i32 s46, vcc_lo, 0xffffff80
	s_mov_b32 m0, s47
	s_nop 0
	buffer_load_dwordx4 v0, s[24:27], s46 offen lds
	s_waitcnt lgkmcnt(8)
	s_barrier
	s_waitcnt lgkmcnt(0)
	v_mfma_f32_16x16x32_bf16 v[126:129], v[132:135], v[148:151], v[126:129]
	v_mfma_f32_16x16x32_bf16 v[122:125], v[140:143], v[148:151], v[122:125]
	v_mfma_f32_16x16x32_bf16 v[118:121], v[132:135], v[156:159], v[118:121]
	v_mfma_f32_16x16x32_bf16 v[114:117], v[140:143], v[156:159], v[114:117]
	v_mfma_f32_16x16x32_bf16 v[110:113], v[132:135], v[164:167], v[110:113]
	v_mfma_f32_16x16x32_bf16 v[106:109], v[140:143], v[164:167], v[106:109]
	v_mfma_f32_16x16x32_bf16 v[102:105], v[132:135], v[172:175], v[102:105]
	v_mfma_f32_16x16x32_bf16 v[98:101], v[140:143], v[172:175], v[98:101]
	v_mfma_f32_16x16x32_bf16 v[126:129], v[136:139], v[152:155], v[126:129]
	v_mfma_f32_16x16x32_bf16 v[122:125], v[144:147], v[152:155], v[122:125]
	v_mfma_f32_16x16x32_bf16 v[118:121], v[136:139], v[160:163], v[118:121]
	v_mfma_f32_16x16x32_bf16 v[114:117], v[144:147], v[160:163], v[114:117]
	v_mfma_f32_16x16x32_bf16 v[110:113], v[136:139], v[168:171], v[110:113]
	v_mfma_f32_16x16x32_bf16 v[106:109], v[144:147], v[168:171], v[106:109]
	v_mfma_f32_16x16x32_bf16 v[102:105], v[136:139], v[176:179], v[102:105]
	v_mfma_f32_16x16x32_bf16 v[98:101], v[144:147], v[176:179], v[98:101]
	s_barrier
	v_readfirstlane_b32 s50, v236
	s_mov_b32 s46, s26
	s_mov_b32 s47, s27
	s_mov_b32 m0, s50
	v_readfirstlane_b32 s55, v235
	ds_read_b128 v[180:183], v188 offset:16384
	ds_read_b128 v[184:187], v188 offset:17408
	ds_read_b128 v[198:201], v188 offset:18432
	ds_read_b128 v[248:251], v188 offset:19456
	buffer_load_dwordx4 v0, s[44:47], s70 offen lds
	s_add_i32 s50, s8, s70
	s_mov_b32 m0, s55
	s_add_i32 s2, s2, 2
	buffer_load_dwordx4 v0, s[44:47], s50 offen lds
	s_barrier
	s_waitcnt lgkmcnt(0)
	v_mfma_f32_16x16x32_bf16 v[94:97], v[180:183], v[148:151], v[94:97]
	v_mfma_f32_16x16x32_bf16 v[90:93], v[198:201], v[148:151], v[90:93]
	v_mfma_f32_16x16x32_bf16 v[86:89], v[180:183], v[156:159], v[86:89]
	v_mfma_f32_16x16x32_bf16 v[82:85], v[198:201], v[156:159], v[82:85]
	v_mfma_f32_16x16x32_bf16 v[78:81], v[180:183], v[164:167], v[78:81]
	v_mfma_f32_16x16x32_bf16 v[74:77], v[198:201], v[164:167], v[74:77]
	v_mfma_f32_16x16x32_bf16 v[70:73], v[180:183], v[172:175], v[70:73]
	v_mfma_f32_16x16x32_bf16 v[66:69], v[198:201], v[172:175], v[66:69]
	v_mfma_f32_16x16x32_bf16 v[94:97], v[184:187], v[152:155], v[94:97]
	v_mfma_f32_16x16x32_bf16 v[90:93], v[248:251], v[152:155], v[90:93]
	v_mfma_f32_16x16x32_bf16 v[86:89], v[184:187], v[160:163], v[86:89]
	v_mfma_f32_16x16x32_bf16 v[82:85], v[248:251], v[160:163], v[82:85]
	v_mfma_f32_16x16x32_bf16 v[78:81], v[184:187], v[168:171], v[78:81]
	v_mfma_f32_16x16x32_bf16 v[74:77], v[248:251], v[168:171], v[74:77]
	v_mfma_f32_16x16x32_bf16 v[70:73], v[184:187], v[176:179], v[70:73]
	v_mfma_f32_16x16x32_bf16 v[66:69], v[248:251], v[176:179], v[66:69]
	v_readfirstlane_b32 s55, v232
	s_mov_b32 m0, s55
	v_readfirstlane_b32 s55, v234
	s_barrier
	ds_read_b128 v[148:151], v237 offset:16384
	ds_read_b128 v[152:155], v237 offset:17408
	ds_read_b128 v[156:159], v237 offset:18432
	ds_read_b128 v[160:163], v237 offset:19456
	ds_read_b128 v[164:167], v237 offset:20480
	ds_read_b128 v[168:171], v237 offset:21504
	ds_read_b128 v[172:175], v237 offset:22528
	ds_read_b128 v[176:179], v237 offset:23552
	buffer_load_dwordx4 v0, s[24:27], s70 offen lds
	s_mov_b32 m0, s55
	s_nop 0
	buffer_load_dwordx4 v0, s[24:27], s50 offen lds
	s_barrier
	s_waitcnt lgkmcnt(0)
	v_mfma_f32_16x16x32_bf16 v[62:65], v[132:135], v[148:151], v[62:65]
	v_mfma_f32_16x16x32_bf16 v[58:61], v[140:143], v[148:151], v[58:61]
	v_mfma_f32_16x16x32_bf16 v[54:57], v[132:135], v[156:159], v[54:57]
	v_mfma_f32_16x16x32_bf16 v[50:53], v[140:143], v[156:159], v[50:53]
	v_mfma_f32_16x16x32_bf16 v[46:49], v[132:135], v[164:167], v[46:49]
	v_mfma_f32_16x16x32_bf16 v[42:45], v[140:143], v[164:167], v[42:45]
	v_mfma_f32_16x16x32_bf16 v[38:41], v[132:135], v[172:175], v[38:41]
	v_mfma_f32_16x16x32_bf16 v[34:37], v[140:143], v[172:175], v[34:37]
	v_mfma_f32_16x16x32_bf16 v[62:65], v[136:139], v[152:155], v[62:65]
	v_mfma_f32_16x16x32_bf16 v[58:61], v[144:147], v[152:155], v[58:61]
	v_mfma_f32_16x16x32_bf16 v[54:57], v[136:139], v[160:163], v[54:57]
	v_mfma_f32_16x16x32_bf16 v[50:53], v[144:147], v[160:163], v[50:53]
	v_mfma_f32_16x16x32_bf16 v[46:49], v[136:139], v[168:171], v[46:49]
	v_mfma_f32_16x16x32_bf16 v[42:45], v[144:147], v[168:171], v[42:45]
	v_mfma_f32_16x16x32_bf16 v[38:41], v[136:139], v[176:179], v[38:41]
	v_mfma_f32_16x16x32_bf16 v[34:37], v[144:147], v[176:179], v[34:37]
	s_barrier
	v_readfirstlane_b32 s55, v233
	s_mov_b32 m0, s55
	v_readfirstlane_b32 s55, v231
	buffer_load_dwordx4 v0, s[44:47], s71 offen lds
	s_mov_b32 m0, s55
	s_nop 0
	buffer_load_dwordx4 v0, s[44:47], vcc_lo offen lds
	s_waitcnt vmcnt(6)
	s_barrier
	v_mfma_f32_16x16x32_bf16 v[30:33], v[180:183], v[148:151], v[30:33]
	v_mfma_f32_16x16x32_bf16 v[26:29], v[198:201], v[148:151], v[26:29]
	v_mfma_f32_16x16x32_bf16 v[22:25], v[180:183], v[156:159], v[22:25]
	v_mfma_f32_16x16x32_bf16 v[18:21], v[198:201], v[156:159], v[18:21]
	v_mfma_f32_16x16x32_bf16 v[14:17], v[180:183], v[164:167], v[14:17]
	v_mfma_f32_16x16x32_bf16 v[10:13], v[198:201], v[164:167], v[10:13]
	v_mfma_f32_16x16x32_bf16 v[6:9], v[180:183], v[172:175], v[6:9]
	v_mfma_f32_16x16x32_bf16 v[2:5], v[198:201], v[172:175], v[2:5]
	v_mfma_f32_16x16x32_bf16 v[30:33], v[184:187], v[152:155], v[30:33]
	v_mfma_f32_16x16x32_bf16 v[26:29], v[248:251], v[152:155], v[26:29]
	v_mfma_f32_16x16x32_bf16 v[22:25], v[184:187], v[160:163], v[22:25]
	v_mfma_f32_16x16x32_bf16 v[18:21], v[248:251], v[160:163], v[18:21]
	v_mfma_f32_16x16x32_bf16 v[14:17], v[184:187], v[168:171], v[14:17]
	v_mfma_f32_16x16x32_bf16 v[10:13], v[248:251], v[168:171], v[10:13]
	v_mfma_f32_16x16x32_bf16 v[6:9], v[184:187], v[176:179], v[6:9]
	v_mfma_f32_16x16x32_bf16 v[2:5], v[248:251], v[176:179], v[2:5]
	s_barrier
	ds_read_b128 v[132:135], v188 offset:32768
	ds_read_b128 v[136:139], v188 offset:33792
	ds_read_b128 v[140:143], v188 offset:34816
	ds_read_b128 v[144:147], v188 offset:35840
	v_readfirstlane_b32 s55, v230
	s_mov_b32 m0, s55
	v_readfirstlane_b32 s55, v205
	ds_read_b128 v[148:151], v237 offset:32768
	ds_read_b128 v[152:155], v237 offset:33792
	ds_read_b128 v[156:159], v237 offset:34816
	ds_read_b128 v[160:163], v237 offset:35840
	ds_read_b128 v[164:167], v237 offset:36864
	ds_read_b128 v[168:171], v237 offset:37888
	ds_read_b128 v[172:175], v237 offset:38912
	ds_read_b128 v[176:179], v237 offset:39936
	buffer_load_dwordx4 v0, s[24:27], s71 offen lds
	s_mov_b32 m0, s55
	s_nop 0
	buffer_load_dwordx4 v0, s[24:27], vcc_lo offen lds
	s_waitcnt lgkmcnt(8)
	s_barrier
	s_waitcnt lgkmcnt(0)
	v_mfma_f32_16x16x32_bf16 v[126:129], v[132:135], v[148:151], v[126:129]
	v_mfma_f32_16x16x32_bf16 v[122:125], v[140:143], v[148:151], v[122:125]
	v_mfma_f32_16x16x32_bf16 v[118:121], v[132:135], v[156:159], v[118:121]
	v_mfma_f32_16x16x32_bf16 v[114:117], v[140:143], v[156:159], v[114:117]
	v_mfma_f32_16x16x32_bf16 v[110:113], v[132:135], v[164:167], v[110:113]
	v_mfma_f32_16x16x32_bf16 v[106:109], v[140:143], v[164:167], v[106:109]
	v_mfma_f32_16x16x32_bf16 v[102:105], v[132:135], v[172:175], v[102:105]
	v_mfma_f32_16x16x32_bf16 v[98:101], v[140:143], v[172:175], v[98:101]
	v_mfma_f32_16x16x32_bf16 v[126:129], v[136:139], v[152:155], v[126:129]
	v_mfma_f32_16x16x32_bf16 v[122:125], v[144:147], v[152:155], v[122:125]
	v_mfma_f32_16x16x32_bf16 v[118:121], v[136:139], v[160:163], v[118:121]
	v_mfma_f32_16x16x32_bf16 v[114:117], v[144:147], v[160:163], v[114:117]
	v_mfma_f32_16x16x32_bf16 v[110:113], v[136:139], v[168:171], v[110:113]
	v_mfma_f32_16x16x32_bf16 v[106:109], v[144:147], v[168:171], v[106:109]
	v_mfma_f32_16x16x32_bf16 v[102:105], v[136:139], v[176:179], v[102:105]
	v_mfma_f32_16x16x32_bf16 v[98:101], v[144:147], v[176:179], v[98:101]
	s_barrier
	v_readfirstlane_b32 s87, v242
	s_add_i32 s55, s70, 0x80
	s_mov_b32 m0, s87
	v_readfirstlane_b32 s87, v243
	ds_read_b128 v[180:183], v188 offset:49152
	ds_read_b128 v[184:187], v188 offset:50176
	ds_read_b128 v[198:201], v188 offset:51200
	ds_read_b128 v[248:251], v188 offset:52224
	buffer_load_dwordx4 v0, s[44:47], s55 offen lds
	s_addk_i32 s50, 0x80
	s_mov_b32 m0, s87
	s_nop 0
	buffer_load_dwordx4 v0, s[44:47], s50 offen lds
	s_barrier
	s_waitcnt lgkmcnt(0)
	v_mfma_f32_16x16x32_bf16 v[94:97], v[180:183], v[148:151], v[94:97]
	v_mfma_f32_16x16x32_bf16 v[90:93], v[198:201], v[148:151], v[90:93]
	v_mfma_f32_16x16x32_bf16 v[86:89], v[180:183], v[156:159], v[86:89]
	v_mfma_f32_16x16x32_bf16 v[82:85], v[198:201], v[156:159], v[82:85]
	v_mfma_f32_16x16x32_bf16 v[78:81], v[180:183], v[164:167], v[78:81]
	v_mfma_f32_16x16x32_bf16 v[74:77], v[198:201], v[164:167], v[74:77]
	v_mfma_f32_16x16x32_bf16 v[70:73], v[180:183], v[172:175], v[70:73]
	v_mfma_f32_16x16x32_bf16 v[66:69], v[198:201], v[172:175], v[66:69]
	v_mfma_f32_16x16x32_bf16 v[94:97], v[184:187], v[152:155], v[94:97]
	v_mfma_f32_16x16x32_bf16 v[90:93], v[248:251], v[152:155], v[90:93]
	v_mfma_f32_16x16x32_bf16 v[86:89], v[184:187], v[160:163], v[86:89]
	v_mfma_f32_16x16x32_bf16 v[82:85], v[248:251], v[160:163], v[82:85]
	v_mfma_f32_16x16x32_bf16 v[78:81], v[184:187], v[168:171], v[78:81]
	v_mfma_f32_16x16x32_bf16 v[74:77], v[248:251], v[168:171], v[74:77]
	v_mfma_f32_16x16x32_bf16 v[70:73], v[184:187], v[176:179], v[70:73]
	v_mfma_f32_16x16x32_bf16 v[66:69], v[248:251], v[176:179], v[66:69]
	v_readfirstlane_b32 s87, v244
	s_mov_b32 m0, s87
	s_barrier
	ds_read_b128 v[148:151], v237 offset:49152
	ds_read_b128 v[152:155], v237 offset:50176
	ds_read_b128 v[156:159], v237 offset:51200
	ds_read_b128 v[160:163], v237 offset:52224
	ds_read_b128 v[164:167], v237 offset:53248
	ds_read_b128 v[168:171], v237 offset:54272
	ds_read_b128 v[172:175], v237 offset:55296
	ds_read_b128 v[176:179], v237 offset:56320
	buffer_load_dwordx4 v0, s[24:27], s55 offen lds
	v_readfirstlane_b32 s55, v245
	s_mov_b32 m0, s55
	s_nop 0
	buffer_load_dwordx4 v0, s[24:27], s50 offen lds
	s_barrier
	s_waitcnt lgkmcnt(0)
	v_mfma_f32_16x16x32_bf16 v[62:65], v[132:135], v[148:151], v[62:65]
	v_mfma_f32_16x16x32_bf16 v[58:61], v[140:143], v[148:151], v[58:61]
	v_mfma_f32_16x16x32_bf16 v[54:57], v[132:135], v[156:159], v[54:57]
	v_mfma_f32_16x16x32_bf16 v[50:53], v[140:143], v[156:159], v[50:53]
	v_mfma_f32_16x16x32_bf16 v[46:49], v[132:135], v[164:167], v[46:49]
	v_mfma_f32_16x16x32_bf16 v[42:45], v[140:143], v[164:167], v[42:45]
	v_mfma_f32_16x16x32_bf16 v[38:41], v[132:135], v[172:175], v[38:41]
	v_mfma_f32_16x16x32_bf16 v[34:37], v[140:143], v[172:175], v[34:37]
	v_mfma_f32_16x16x32_bf16 v[62:65], v[136:139], v[152:155], v[62:65]
	v_mfma_f32_16x16x32_bf16 v[58:61], v[144:147], v[152:155], v[58:61]
	v_mfma_f32_16x16x32_bf16 v[54:57], v[136:139], v[160:163], v[54:57]
	v_mfma_f32_16x16x32_bf16 v[50:53], v[144:147], v[160:163], v[50:53]
	v_mfma_f32_16x16x32_bf16 v[46:49], v[136:139], v[168:171], v[46:49]
	v_mfma_f32_16x16x32_bf16 v[42:45], v[144:147], v[168:171], v[42:45]
	v_mfma_f32_16x16x32_bf16 v[38:41], v[136:139], v[176:179], v[38:41]
	v_mfma_f32_16x16x32_bf16 v[34:37], v[144:147], v[176:179], v[34:37]
	s_barrier
	v_readfirstlane_b32 s50, v246
	s_addk_i32 s71, 0x80
	s_mov_b32 m0, s50
	v_readfirstlane_b32 s50, v247
	buffer_load_dwordx4 v0, s[44:47], s71 offen lds
	s_addk_i32 vcc_lo, 0x80
	s_mov_b32 m0, s50
	s_nop 0
	buffer_load_dwordx4 v0, s[44:47], vcc_lo offen lds
	s_waitcnt vmcnt(6)
	s_barrier
	v_mfma_f32_16x16x32_bf16 v[30:33], v[180:183], v[148:151], v[30:33]
	v_mfma_f32_16x16x32_bf16 v[26:29], v[198:201], v[148:151], v[26:29]
	v_mfma_f32_16x16x32_bf16 v[22:25], v[180:183], v[156:159], v[22:25]
	v_mfma_f32_16x16x32_bf16 v[18:21], v[198:201], v[156:159], v[18:21]
	v_mfma_f32_16x16x32_bf16 v[14:17], v[180:183], v[164:167], v[14:17]
	v_mfma_f32_16x16x32_bf16 v[10:13], v[198:201], v[164:167], v[10:13]
	v_mfma_f32_16x16x32_bf16 v[6:9], v[180:183], v[172:175], v[6:9]
	v_mfma_f32_16x16x32_bf16 v[2:5], v[198:201], v[172:175], v[2:5]
	v_mfma_f32_16x16x32_bf16 v[30:33], v[184:187], v[152:155], v[30:33]
	v_mfma_f32_16x16x32_bf16 v[26:29], v[248:251], v[152:155], v[26:29]
	v_mfma_f32_16x16x32_bf16 v[22:25], v[184:187], v[160:163], v[22:25]
	v_mfma_f32_16x16x32_bf16 v[18:21], v[248:251], v[160:163], v[18:21]
	v_mfma_f32_16x16x32_bf16 v[14:17], v[184:187], v[168:171], v[14:17]
	v_mfma_f32_16x16x32_bf16 v[10:13], v[248:251], v[168:171], v[10:13]
	v_mfma_f32_16x16x32_bf16 v[6:9], v[184:187], v[176:179], v[6:9]
	v_mfma_f32_16x16x32_bf16 v[2:5], v[248:251], v[176:179], v[2:5]
	s_addk_i32 s70, 0x100
	s_mov_b64 s[46:47], 0x200
	v_lshl_add_u64 v[130:131], v[130:131], 0, s[46:47]
	s_cmp_ge_i32 s2, s59
	s_cbranch_scc1 .Lrot_exit
	s_andn2_b64 vcc, exec, s[30:31]
	s_cbranch_vccz .Lrot_seam
	s_barrier
	s_branch .LBB0_254

.LBB0_262:
	s_and_b64 s[6:7], exec, s[6:7]
	s_or_b64 s[92:93], s[6:7], s[92:93]
	s_lshl_b32 s2, s33, 7
	s_add_i32 s2, s58, s2
	v_readfirstlane_b32 s6, v241
	v_add_u32_e32 v202, v239, v238
	s_addk_i32 s2, 0xff80
	s_mov_b32 m0, s6
	v_readfirstlane_b32 s6, v240
	ds_read_b128 v[130:133], v202
	ds_read_b128 v[134:137], v202 offset:1024
	ds_read_b128 v[138:141], v202 offset:2048
	ds_read_b128 v[142:145], v202 offset:3072
	ds_read_b128 v[146:149], v237
	ds_read_b128 v[150:153], v237 offset:1024
	ds_read_b128 v[154:157], v237 offset:2048
	ds_read_b128 v[158:161], v237 offset:3072
	ds_read_b128 v[162:165], v237 offset:4096
	ds_read_b128 v[166:169], v237 offset:5120
	ds_read_b128 v[170:173], v237 offset:6144
	ds_read_b128 v[174:177], v237 offset:7168
	buffer_load_dwordx4 v0, s[24:27], s2 offen lds
	s_add_i32 s2, s2, s8
	s_mov_b32 m0, s6
	s_nop 0
	buffer_load_dwordx4 v0, s[24:27], s2 offen lds
	s_barrier
	s_waitcnt lgkmcnt(0)
	v_mfma_f32_16x16x32_bf16 v[126:129], v[130:133], v[146:149], v[126:129]
	v_mfma_f32_16x16x32_bf16 v[122:125], v[138:141], v[146:149], v[122:125]
	v_mfma_f32_16x16x32_bf16 v[118:121], v[130:133], v[154:157], v[118:121]
	v_mfma_f32_16x16x32_bf16 v[114:117], v[138:141], v[154:157], v[114:117]
	v_mfma_f32_16x16x32_bf16 v[110:113], v[130:133], v[162:165], v[110:113]
	v_mfma_f32_16x16x32_bf16 v[106:109], v[138:141], v[162:165], v[106:109]
	v_mfma_f32_16x16x32_bf16 v[102:105], v[130:133], v[170:173], v[102:105]
	v_mfma_f32_16x16x32_bf16 v[98:101], v[138:141], v[170:173], v[98:101]
	v_mfma_f32_16x16x32_bf16 v[126:129], v[134:137], v[150:153], v[126:129]
	v_mfma_f32_16x16x32_bf16 v[122:125], v[142:145], v[150:153], v[122:125]
	v_mfma_f32_16x16x32_bf16 v[118:121], v[134:137], v[158:161], v[118:121]
	v_mfma_f32_16x16x32_bf16 v[114:117], v[142:145], v[158:161], v[114:117]
	v_mfma_f32_16x16x32_bf16 v[110:113], v[134:137], v[166:169], v[110:113]
	v_mfma_f32_16x16x32_bf16 v[106:109], v[142:145], v[166:169], v[106:109]
	v_mfma_f32_16x16x32_bf16 v[102:105], v[134:137], v[174:177], v[102:105]
	v_mfma_f32_16x16x32_bf16 v[98:101], v[142:145], v[174:177], v[98:101]
	s_barrier
	ds_read_b128 v[178:181], v202 offset:16384
	ds_read_b128 v[182:185], v202 offset:17408
	ds_read_b128 v[186:189], v202 offset:18432
	ds_read_b128 v[198:201], v202 offset:19456
	s_barrier
	s_waitcnt lgkmcnt(0)
	v_mfma_f32_16x16x32_bf16 v[94:97], v[178:181], v[146:149], v[94:97]
	v_mfma_f32_16x16x32_bf16 v[90:93], v[186:189], v[146:149], v[90:93]
	v_mfma_f32_16x16x32_bf16 v[86:89], v[178:181], v[154:157], v[86:89]
	v_mfma_f32_16x16x32_bf16 v[82:85], v[186:189], v[154:157], v[82:85]
	v_mfma_f32_16x16x32_bf16 v[78:81], v[178:181], v[162:165], v[78:81]
	v_mfma_f32_16x16x32_bf16 v[74:77], v[186:189], v[162:165], v[74:77]
	v_mfma_f32_16x16x32_bf16 v[70:73], v[178:181], v[170:173], v[70:73]
	v_mfma_f32_16x16x32_bf16 v[66:69], v[186:189], v[170:173], v[66:69]
	v_mfma_f32_16x16x32_bf16 v[94:97], v[182:185], v[150:153], v[94:97]
	v_mfma_f32_16x16x32_bf16 v[90:93], v[198:201], v[150:153], v[90:93]
	v_mfma_f32_16x16x32_bf16 v[86:89], v[182:185], v[158:161], v[86:89]
	v_mfma_f32_16x16x32_bf16 v[82:85], v[198:201], v[158:161], v[82:85]
	v_mfma_f32_16x16x32_bf16 v[78:81], v[182:185], v[166:169], v[78:81]
	v_mfma_f32_16x16x32_bf16 v[74:77], v[198:201], v[166:169], v[74:77]
	v_mfma_f32_16x16x32_bf16 v[70:73], v[182:185], v[174:177], v[70:73]
	v_mfma_f32_16x16x32_bf16 v[66:69], v[198:201], v[174:177], v[66:69]
	s_barrier
	ds_read_b128 v[146:149], v237 offset:16384
	ds_read_b128 v[150:153], v237 offset:17408
	ds_read_b128 v[154:157], v237 offset:18432
	ds_read_b128 v[158:161], v237 offset:19456
	ds_read_b128 v[162:165], v237 offset:20480
	ds_read_b128 v[166:169], v237 offset:21504
	ds_read_b128 v[170:173], v237 offset:22528
	ds_read_b128 v[174:177], v237 offset:23552
	s_waitcnt vmcnt(4)
	s_barrier
	s_waitcnt lgkmcnt(0)
	v_mfma_f32_16x16x32_bf16 v[62:65], v[130:133], v[146:149], v[62:65]
	v_mfma_f32_16x16x32_bf16 v[58:61], v[138:141], v[146:149], v[58:61]
	v_mfma_f32_16x16x32_bf16 v[54:57], v[130:133], v[154:157], v[54:57]
	v_mfma_f32_16x16x32_bf16 v[50:53], v[138:141], v[154:157], v[50:53]
	v_mfma_f32_16x16x32_bf16 v[46:49], v[130:133], v[162:165], v[46:49]
	v_mfma_f32_16x16x32_bf16 v[42:45], v[138:141], v[162:165], v[42:45]
	v_mfma_f32_16x16x32_bf16 v[38:41], v[130:133], v[170:173], v[38:41]
	v_mfma_f32_16x16x32_bf16 v[34:37], v[138:141], v[170:173], v[34:37]
	v_mfma_f32_16x16x32_bf16 v[62:65], v[134:137], v[150:153], v[62:65]
	v_mfma_f32_16x16x32_bf16 v[58:61], v[142:145], v[150:153], v[58:61]
	v_mfma_f32_16x16x32_bf16 v[54:57], v[134:137], v[158:161], v[54:57]
	v_mfma_f32_16x16x32_bf16 v[50:53], v[142:145], v[158:161], v[50:53]
	v_mfma_f32_16x16x32_bf16 v[46:49], v[134:137], v[166:169], v[46:49]
	v_mfma_f32_16x16x32_bf16 v[42:45], v[142:145], v[166:169], v[42:45]
	v_mfma_f32_16x16x32_bf16 v[38:41], v[134:137], v[174:177], v[38:41]
	v_mfma_f32_16x16x32_bf16 v[34:37], v[142:145], v[174:177], v[34:37]
	v_mfma_f32_16x16x32_bf16 v[30:33], v[178:181], v[146:149], v[30:33]
	v_mfma_f32_16x16x32_bf16 v[26:29], v[186:189], v[146:149], v[26:29]
	v_mfma_f32_16x16x32_bf16 v[22:25], v[178:181], v[154:157], v[22:25]
	v_mfma_f32_16x16x32_bf16 v[18:21], v[186:189], v[154:157], v[18:21]
	v_mfma_f32_16x16x32_bf16 v[14:17], v[178:181], v[162:165], v[14:17]
	v_mfma_f32_16x16x32_bf16 v[10:13], v[186:189], v[162:165], v[10:13]
	v_mfma_f32_16x16x32_bf16 v[6:9], v[178:181], v[170:173], v[6:9]
	v_mfma_f32_16x16x32_bf16 v[2:5], v[186:189], v[170:173], v[2:5]
	v_mfma_f32_16x16x32_bf16 v[30:33], v[182:185], v[150:153], v[30:33]
	v_mfma_f32_16x16x32_bf16 v[26:29], v[198:201], v[150:153], v[26:29]
	v_mfma_f32_16x16x32_bf16 v[22:25], v[182:185], v[158:161], v[22:25]
	v_mfma_f32_16x16x32_bf16 v[18:21], v[198:201], v[158:161], v[18:21]
	v_mfma_f32_16x16x32_bf16 v[14:17], v[182:185], v[166:169], v[14:17]
	v_mfma_f32_16x16x32_bf16 v[10:13], v[198:201], v[166:169], v[10:13]
	v_mfma_f32_16x16x32_bf16 v[6:9], v[182:185], v[174:177], v[6:9]
	v_mfma_f32_16x16x32_bf16 v[2:5], v[198:201], v[174:177], v[2:5]
	s_barrier
	ds_read_b128 v[130:133], v202 offset:32768
	ds_read_b128 v[134:137], v202 offset:33792
	ds_read_b128 v[138:141], v202 offset:34816
	ds_read_b128 v[142:145], v202 offset:35840
	ds_read_b128 v[146:149], v237 offset:32768
	ds_read_b128 v[150:153], v237 offset:33792
	ds_read_b128 v[154:157], v237 offset:34816
	ds_read_b128 v[158:161], v237 offset:35840
	ds_read_b128 v[162:165], v237 offset:36864
	ds_read_b128 v[166:169], v237 offset:37888
	ds_read_b128 v[170:173], v237 offset:38912
	ds_read_b128 v[174:177], v237 offset:39936
	s_waitcnt vmcnt(2)
	s_barrier
	s_waitcnt lgkmcnt(0)
	v_mfma_f32_16x16x32_bf16 v[126:129], v[130:133], v[146:149], v[126:129]
	v_mfma_f32_16x16x32_bf16 v[122:125], v[138:141], v[146:149], v[122:125]
	v_mfma_f32_16x16x32_bf16 v[118:121], v[130:133], v[154:157], v[118:121]
	v_mfma_f32_16x16x32_bf16 v[114:117], v[138:141], v[154:157], v[114:117]
	v_mfma_f32_16x16x32_bf16 v[110:113], v[130:133], v[162:165], v[110:113]
	v_mfma_f32_16x16x32_bf16 v[106:109], v[138:141], v[162:165], v[106:109]
	v_mfma_f32_16x16x32_bf16 v[102:105], v[130:133], v[170:173], v[102:105]
	v_mfma_f32_16x16x32_bf16 v[98:101], v[138:141], v[170:173], v[98:101]
	v_mfma_f32_16x16x32_bf16 v[126:129], v[134:137], v[150:153], v[126:129]
	v_mfma_f32_16x16x32_bf16 v[122:125], v[142:145], v[150:153], v[122:125]
	v_mfma_f32_16x16x32_bf16 v[118:121], v[134:137], v[158:161], v[118:121]
	v_mfma_f32_16x16x32_bf16 v[114:117], v[142:145], v[158:161], v[114:117]
	v_mfma_f32_16x16x32_bf16 v[110:113], v[134:137], v[166:169], v[110:113]
	v_mfma_f32_16x16x32_bf16 v[106:109], v[142:145], v[166:169], v[106:109]
	v_mfma_f32_16x16x32_bf16 v[102:105], v[134:137], v[174:177], v[102:105]
	v_mfma_f32_16x16x32_bf16 v[98:101], v[142:145], v[174:177], v[98:101]
	s_barrier
	ds_read_b128 v[178:181], v202 offset:49152
	ds_read_b128 v[182:185], v202 offset:50176
	ds_read_b128 v[186:189], v202 offset:51200
	ds_read_b128 v[198:201], v202 offset:52224
	s_waitcnt vmcnt(0)
	s_barrier
	s_waitcnt lgkmcnt(0)
	v_mfma_f32_16x16x32_bf16 v[94:97], v[178:181], v[146:149], v[94:97]
	v_mfma_f32_16x16x32_bf16 v[90:93], v[186:189], v[146:149], v[90:93]
	v_mfma_f32_16x16x32_bf16 v[86:89], v[178:181], v[154:157], v[86:89]
	v_mfma_f32_16x16x32_bf16 v[82:85], v[186:189], v[154:157], v[82:85]
	v_mfma_f32_16x16x32_bf16 v[78:81], v[178:181], v[162:165], v[78:81]
	v_mfma_f32_16x16x32_bf16 v[74:77], v[186:189], v[162:165], v[74:77]
	v_mfma_f32_16x16x32_bf16 v[70:73], v[178:181], v[170:173], v[70:73]
	v_mfma_f32_16x16x32_bf16 v[66:69], v[186:189], v[170:173], v[66:69]
	v_mfma_f32_16x16x32_bf16 v[94:97], v[182:185], v[150:153], v[94:97]
	v_mfma_f32_16x16x32_bf16 v[90:93], v[198:201], v[150:153], v[90:93]
	v_mfma_f32_16x16x32_bf16 v[86:89], v[182:185], v[158:161], v[86:89]
	v_mfma_f32_16x16x32_bf16 v[82:85], v[198:201], v[158:161], v[82:85]
	v_mfma_f32_16x16x32_bf16 v[78:81], v[182:185], v[166:169], v[78:81]
	v_mfma_f32_16x16x32_bf16 v[74:77], v[198:201], v[166:169], v[74:77]
	v_mfma_f32_16x16x32_bf16 v[70:73], v[182:185], v[174:177], v[70:73]
	v_mfma_f32_16x16x32_bf16 v[66:69], v[198:201], v[174:177], v[66:69]
	s_barrier
	ds_read_b128 v[146:149], v237 offset:49152
	ds_read_b128 v[150:153], v237 offset:50176
	ds_read_b128 v[154:157], v237 offset:51200
	ds_read_b128 v[158:161], v237 offset:52224
	ds_read_b128 v[162:165], v237 offset:53248
	ds_read_b128 v[166:169], v237 offset:54272
	ds_read_b128 v[170:173], v237 offset:55296
	ds_read_b128 v[174:177], v237 offset:56320
	s_barrier
	s_waitcnt lgkmcnt(0)
	v_mfma_f32_16x16x32_bf16 v[62:65], v[130:133], v[146:149], v[62:65]
	v_mfma_f32_16x16x32_bf16 v[58:61], v[138:141], v[146:149], v[58:61]
	v_mfma_f32_16x16x32_bf16 v[54:57], v[130:133], v[154:157], v[54:57]
	v_mfma_f32_16x16x32_bf16 v[50:53], v[138:141], v[154:157], v[50:53]
	v_mfma_f32_16x16x32_bf16 v[46:49], v[130:133], v[162:165], v[46:49]
	v_mfma_f32_16x16x32_bf16 v[42:45], v[138:141], v[162:165], v[42:45]
	v_mfma_f32_16x16x32_bf16 v[38:41], v[130:133], v[170:173], v[38:41]
	v_mfma_f32_16x16x32_bf16 v[34:37], v[138:141], v[170:173], v[34:37]
	v_mfma_f32_16x16x32_bf16 v[62:65], v[134:137], v[150:153], v[62:65]
	v_mfma_f32_16x16x32_bf16 v[58:61], v[142:145], v[150:153], v[58:61]
	v_mfma_f32_16x16x32_bf16 v[54:57], v[134:137], v[158:161], v[54:57]
	v_mfma_f32_16x16x32_bf16 v[50:53], v[142:145], v[158:161], v[50:53]
	v_mfma_f32_16x16x32_bf16 v[46:49], v[134:137], v[166:169], v[46:49]
	v_mfma_f32_16x16x32_bf16 v[42:45], v[142:145], v[166:169], v[42:45]
	v_mfma_f32_16x16x32_bf16 v[38:41], v[134:137], v[174:177], v[38:41]
	v_mfma_f32_16x16x32_bf16 v[34:37], v[142:145], v[174:177], v[34:37]
	v_mfma_f32_16x16x32_bf16 v[30:33], v[178:181], v[146:149], v[30:33]
	v_mfma_f32_16x16x32_bf16 v[26:29], v[186:189], v[146:149], v[26:29]
	v_mfma_f32_16x16x32_bf16 v[22:25], v[178:181], v[154:157], v[22:25]
	v_mfma_f32_16x16x32_bf16 v[18:21], v[186:189], v[154:157], v[18:21]
	v_mfma_f32_16x16x32_bf16 v[14:17], v[178:181], v[162:165], v[14:17]
	v_mfma_f32_16x16x32_bf16 v[10:13], v[186:189], v[162:165], v[10:13]
	v_mfma_f32_16x16x32_bf16 v[6:9], v[178:181], v[170:173], v[6:9]
	v_mfma_f32_16x16x32_bf16 v[2:5], v[186:189], v[170:173], v[2:5]
	v_mfma_f32_16x16x32_bf16 v[30:33], v[182:185], v[150:153], v[30:33]
	v_mfma_f32_16x16x32_bf16 v[26:29], v[198:201], v[150:153], v[26:29]
	v_mfma_f32_16x16x32_bf16 v[22:25], v[182:185], v[158:161], v[22:25]
	v_mfma_f32_16x16x32_bf16 v[18:21], v[198:201], v[158:161], v[18:21]
	v_mfma_f32_16x16x32_bf16 v[14:17], v[182:185], v[166:169], v[14:17]
	v_mfma_f32_16x16x32_bf16 v[10:13], v[198:201], v[166:169], v[10:13]
	v_mfma_f32_16x16x32_bf16 v[6:9], v[182:185], v[174:177], v[6:9]
	v_mfma_f32_16x16x32_bf16 v[2:5], v[198:201], v[174:177], v[2:5]
	s_movk_i32 s2, 0x100
	v_cmp_gt_u32_e32 vcc, s2, v204
	s_barrier
	s_and_saveexec_b64 s[6:7], vcc
	s_cbranch_execz .LBB0_264
	s_barrier
